# v125 plus reversed priority flips in the DA loop: prio 1 across the softmax VALU regions, prio 0 across the PV+QK MFMA regions
# baseline (speedup 1.0000x reference)
; __device__ __forceinline__ unsigned cvtpk(float lo, float hi) { f32x2_t v = {lo, hi}; bf16x2_t b = __builtin_convertvector(v, bf16x2_t); return __builtin_bit_cast(unsigned, b); }
; #define SBAR() __builtin_amdgcn_sched_barrier(0)
; template <bool ISSUE> ...
;     ...
;     const float off = mref - cb;
;     s0 = s0 - off; s1 = s1 - off;
; #pragma unroll
;     for (int r = 0; r < 16; ++r) { s0[r] = __builtin_amdgcn_exp2f(s0[r]); s1[r] = __builtin_amdgcn_exp2f(s1[r]); }
;     {
;         const f32x16 sm = s0 + s1;
;         lsum += ((sm[0] + sm[1]) + (sm[2] + sm[3])) + ((sm[4] + sm[5]) + (sm[6] + sm[7])) + (((sm[8] + sm[9]) + (sm[10] + sm[11])) + ((sm[12] + sm[13]) + (sm[14] + sm[15])));
;     }
;     bf16x8 p[4];
;     {
;         u32x4 w;
;         w.x = cvtpk(s0[0], s0[1]); w.y = cvtpk(s0[2], s0[3]); w.z = cvtpk(s0[4], s0[5]); w.w = cvtpk(s0[6], s0[7]); p[0] = __builtin_bit_cast(bf16x8, w);
;         w.x = cvtpk(s0[8], s0[9]); w.y = cvtpk(s0[10], s0[11]); w.z = cvtpk(s0[12], s0[13]); w.w = cvtpk(s0[14], s0[15]); p[1] = __builtin_bit_cast(bf16x8, w);
;         w.x = cvtpk(s1[0], s1[1]); w.y = cvtpk(s1[2], s1[3]); w.z = cvtpk(s1[4], s1[5]); w.w = cvtpk(s1[6], s1[7]); p[2] = __builtin_bit_cast(bf16x8, w);
;         w.x = cvtpk(s1[8], s1[9]); w.y = cvtpk(s1[10], s1[11]); w.z = cvtpk(s1[12], s1[13]); w.w = cvtpk(s1[14], s1[15]); p[3] = __builtin_bit_cast(bf16x8, w);
;     }
;     v_reads(vb, lds, vaddr, vb_ + 4096);
;     SBAR();
;     pv_rest<128>(o, p, va, vb, lds, vaddr, vb_);
; __device__ __forceinline__ void flash_da2(LAS unsigned char* lds, const bf16* __restrict__ Qw, const bf16* __restrict__ Kb, const bf16* __restrict__ VTb,
;                                           int NT, int qpos_w, f32x16 (&o)[4], float& mref, float& lsum) {
;     ...
;     for (int t = 0; t < NT; t += 2) {
;         da_tile<true>(lds, t, NT, qpos_w, r32, hi, qf, kaddr, vaddr, ksrc, vsrc, kdst, vdst, cls_cur, cb, o, mref, lsum);
;         da_tile<false>(lds, t + 1, NT, qpos_w, r32, hi, qf, kaddr, vaddr, ksrc, vsrc, kdst, vdst, cls_cur, cb, o, mref, lsum);
;         asm volatile("s_waitcnt vmcnt(0) lgkmcnt(0)\n\ts_barrier" ::: "memory");
;     }
.LBB0_427:
	v_sub_f32_e32 v14, v224, v225
	v_sub_f32_e32 v140, v109, v14
	v_sub_f32_e32 v105, v105, v14
	v_sub_f32_e32 v104, v104, v14
	v_sub_f32_e32 v15, v97, v14
	v_sub_f32_e32 v96, v96, v14
	v_sub_f32_e32 v109, v89, v14
	v_sub_f32_e32 v97, v88, v14
	v_sub_f32_e32 v81, v81, v14
	v_sub_f32_e32 v80, v80, v14
	v_sub_f32_e32 v133, v111, v14
	v_sub_f32_e32 v134, v110, v14
	v_sub_f32_e32 v132, v108, v14
	v_sub_f32_e32 v107, v107, v14
	v_sub_f32_e32 v106, v106, v14
	v_sub_f32_e32 v103, v103, v14
	v_sub_f32_e32 v102, v102, v14
	v_sub_f32_e32 v101, v101, v14
	v_sub_f32_e32 v100, v100, v14
	v_sub_f32_e32 v99, v99, v14
	v_sub_f32_e32 v98, v98, v14
	v_sub_f32_e32 v135, v95, v14
	v_sub_f32_e32 v141, v94, v14
	v_sub_f32_e32 v142, v93, v14
	v_sub_f32_e32 v143, v92, v14
	v_sub_f32_e32 v111, v91, v14
	v_sub_f32_e32 v110, v90, v14
	v_sub_f32_e32 v95, v87, v14
	v_sub_f32_e32 v87, v86, v14
	v_sub_f32_e32 v86, v85, v14
	v_sub_f32_e32 v85, v84, v14
	v_sub_f32_e32 v84, v83, v14
	v_sub_f32_e32 v83, v82, v14
	v_exp_f32_e32 v14, v96
	v_exp_f32_e32 v88, v80
	v_exp_f32_e32 v15, v15
	v_exp_f32_e32 v89, v81
	v_exp_f32_e32 v96, v104
	v_exp_f32_e32 v108, v97
	v_exp_f32_e32 v97, v105
	v_exp_f32_e32 v109, v109
	v_exp_f32_e32 v82, v98
	v_exp_f32_e32 v90, v83
	v_exp_f32_e32 v83, v99
	v_exp_f32_e32 v91, v84
	v_exp_f32_e32 v98, v106
	v_exp_f32_e32 v110, v110
	v_exp_f32_e32 v99, v107
	v_exp_f32_e32 v111, v111
	v_exp_f32_e32 v84, v100
	v_exp_f32_e32 v92, v85
	v_exp_f32_e32 v85, v101
	v_exp_f32_e32 v93, v86
	v_exp_f32_e32 v94, v87
	v_exp_f32_e32 v87, v103
	v_exp_f32_e32 v100, v132
	v_exp_f32_e32 v132, v143
	v_exp_f32_e32 v103, v133
	v_exp_f32_e32 v101, v140
	v_exp_f32_e32 v133, v142
	v_exp_f32_e32 v86, v102
	v_exp_f32_e32 v95, v95
	v_exp_f32_e32 v102, v134
	v_exp_f32_e32 v134, v141
	v_exp_f32_e32 v135, v135
	v_pk_add_f32 v[146:147], v[88:89], v[14:15]
	v_pk_add_f32 v[164:165], v[108:109], v[96:97]
	v_pk_add_f32 v[142:143], v[90:91], v[82:83]
	v_pk_add_f32 v[144:145], v[110:111], v[98:99]
	v_mov_b32_e32 v166, v146
	v_mov_b32_e32 v167, v164
	v_mov_b32_e32 v164, v147
	v_pk_add_f32 v[106:107], v[92:93], v[84:85]
	v_pk_add_f32 v[140:141], v[132:133], v[100:101]
	v_pk_add_f32 v[146:147], v[166:167], v[164:165]
	v_mov_b32_e32 v164, v142
	v_mov_b32_e32 v165, v144
	v_mov_b32_e32 v144, v143
	v_pk_add_f32 v[80:81], v[94:95], v[86:87]
	v_pk_add_f32 v[104:105], v[134:135], v[102:103]
	v_pk_add_f32 v[142:143], v[164:165], v[144:145]
	v_mov_b32_e32 v144, v106
	v_mov_b32_e32 v145, v140
	v_mov_b32_e32 v140, v107
	v_pk_add_f32 v[106:107], v[144:145], v[140:141]
	v_mov_b32_e32 v140, v80
	v_mov_b32_e32 v141, v104
	v_mov_b32_e32 v104, v81
	v_pk_add_f32 v[80:81], v[140:141], v[104:105]
	v_pk_add_f32 v[142:143], v[146:147], v[142:143]
	v_pk_add_f32 v[80:81], v[106:107], v[80:81]
	v_cvt_pk_bf16_f32 v88, v88, v89
	v_pk_add_f32 v[80:81], v[142:143], v[80:81]
	v_cvt_pk_bf16_f32 v89, v90, v91
	v_add_f32_e32 v80, v80, v81
	v_cvt_pk_bf16_f32 v81, v82, v83
	v_cvt_pk_bf16_f32 v82, v84, v85
	v_cvt_pk_bf16_f32 v83, v86, v87
	v_cvt_pk_bf16_f32 v84, v96, v97
	v_cvt_pk_bf16_f32 v85, v98, v99
	v_cvt_pk_bf16_f32 v86, v100, v101
	v_cvt_pk_bf16_f32 v87, v102, v103
	v_cvt_pk_bf16_f32 v90, v92, v93
	v_cvt_pk_bf16_f32 v91, v94, v95
	ds_read_b128 v[92:95], v136 offset:36864
	ds_read_b128 v[96:99], v137 offset:36864
	ds_read_b128 v[100:103], v138 offset:36864
	ds_read_b128 v[104:107], v139 offset:36864
	v_add_f32_e32 v0, v0, v80
	v_cvt_pk_bf16_f32 v80, v14, v15
	v_cvt_pk_bf16_f32 v108, v108, v109
	v_cvt_pk_bf16_f32 v109, v110, v111
	v_cvt_pk_bf16_f32 v110, v132, v133
	v_cvt_pk_bf16_f32 v111, v134, v135
	s_setprio 0
	s_waitcnt lgkmcnt(7)
	v_mfma_f32_32x32x16_bf16 v[64:79], v[6:9], v[80:83], v[64:79]
	s_waitcnt lgkmcnt(6)
	v_mfma_f32_32x32x16_bf16 v[64:79], v[2:5], v[84:87], v[64:79]
	s_waitcnt lgkmcnt(5)
	v_mfma_f32_32x32x16_bf16 v[64:79], v[10:13], v[88:91], v[64:79]
	s_waitcnt lgkmcnt(4)
	v_mfma_f32_32x32x16_bf16 v[64:79], v[128:131], v[108:111], v[64:79]
	ds_read_b128 v[2:5], v136 offset:40960
	ds_read_b128 v[6:9], v137 offset:40960
	ds_read_b128 v[10:13], v138 offset:40960
	ds_read_b128 v[128:131], v139 offset:40960
	s_waitcnt lgkmcnt(7)
	v_mfma_f32_32x32x16_bf16 v[48:63], v[92:95], v[80:83], v[48:63]
	s_waitcnt lgkmcnt(6)
	v_mfma_f32_32x32x16_bf16 v[48:63], v[96:99], v[84:87], v[48:63]
	s_waitcnt lgkmcnt(5)
	v_mfma_f32_32x32x16_bf16 v[48:63], v[100:103], v[88:91], v[48:63]
	s_waitcnt lgkmcnt(4)
	v_mfma_f32_32x32x16_bf16 v[48:63], v[104:107], v[108:111], v[48:63]
	ds_read_b128 v[92:95], v136 offset:45056
	ds_read_b128 v[96:99], v137 offset:45056
	ds_read_b128 v[100:103], v138 offset:45056
	ds_read_b128 v[104:107], v139 offset:45056
	s_waitcnt lgkmcnt(7)
	v_mfma_f32_32x32x16_bf16 v[32:47], v[2:5], v[80:83], v[32:47]
	s_waitcnt lgkmcnt(6)
	v_mfma_f32_32x32x16_bf16 v[32:47], v[6:9], v[84:87], v[32:47]
	s_waitcnt lgkmcnt(5)
	v_mfma_f32_32x32x16_bf16 v[32:47], v[10:13], v[88:91], v[32:47]
	s_waitcnt lgkmcnt(4)
	v_mfma_f32_32x32x16_bf16 v[32:47], v[128:131], v[108:111], v[32:47]
	s_waitcnt lgkmcnt(3)
	v_mfma_f32_32x32x16_bf16 v[16:31], v[92:95], v[80:83], v[16:31]
	s_waitcnt vmcnt(0) lgkmcnt(0)
	s_barrier
	s_add_i32 s8, s8, 2
	s_mov_b64 s[62:63], 0x8000
	s_addk_i32 s53, 0x80
	v_lshl_add_u64 v[160:161], v[160:161], 0, s[62:63]
	v_lshl_add_u64 v[162:163], v[162:163], 0, s[40:41]
	v_add_u32_e32 v223, 0x200, v223
	s_waitcnt lgkmcnt(2)
	v_mfma_f32_32x32x16_bf16 v[16:31], v[96:99], v[84:87], v[16:31]
	s_cmp_lt_u32 s66, s90
	s_waitcnt lgkmcnt(1)
	v_mfma_f32_32x32x16_bf16 v[16:31], v[100:103], v[88:91], v[16:31]
	s_waitcnt lgkmcnt(0)
	v_mfma_f32_32x32x16_bf16 v[16:31], v[104:107], v[108:111], v[16:31]
	s_cbranch_scc0 .LBB0_450

; #define LAS __attribute__((address_space(3)))
; #define SBAR() __builtin_amdgcn_sched_barrier(0)
; template <bool ISSUE> ...
;     ...
;     s0 = __builtin_amdgcn_mfma_f32_32x32x16_bf16(kf[0], qf[0], f32x16{}, 0, 0, 0);
;     s1 = __builtin_amdgcn_mfma_f32_32x32x16_bf16(kf[1], qf[0], f32x16{}, 0, 0, 0);
; #pragma unroll
;     for (int d0 = 1; d0 < 4; ++d0) {
;         s0 = __builtin_amdgcn_mfma_f32_32x32x16_bf16(kf[2 * d0], qf[d0], s0, 0, 0, 0);
;         s1 = __builtin_amdgcn_mfma_f32_32x32x16_bf16(kf[2 * d0 + 1], qf[d0], s1, 0, 0, 0);
;     }
;     bf16x8 va[4], vb[4];
;     v_reads(va, lds, vaddr, vb_);
;     SBAR();
;     if (cls == 0) {
;         int a0 = (kt + 16 * hi - (qpos_w + r32) + 129) * 4 + A_BT; asm volatile("" : "+v"(a0));
; #pragma unroll
;         for (int rg = 0; rg < 4; ++rg) {
; #pragma unroll
;             for (int r = 4 * rg; r < 4 * rg + 4; ++r) {
;                 const int aa = min(max(a0 + 4 * r, A_BT), A_BT + 258 * 4), ab = min(max(a0 + 4 * r + 128, A_BT), A_BT + 258 * 4);
;                 s0[r] += *(const LAS float*)(lds + aa);
;                 s1[r] += *(const LAS float*)(lds + ab);
;             }
;             SBAR();
;         }
.LBB0_434:
	s_waitcnt lgkmcnt(7)
	v_mfma_f32_32x32x16_bf16 v[96:111], v[80:83], v[112:115], 0
	s_add_i32 s67, s67, s66
	s_waitcnt lgkmcnt(6)
	v_mfma_f32_32x32x16_bf16 v[80:95], v[84:87], v[112:115], 0
	s_waitcnt lgkmcnt(5)
	v_mfma_f32_32x32x16_bf16 v[96:111], v[136:139], v[116:119], v[96:111]
	v_add_u32_e32 v136, s67, v212
	v_add_u32_e32 v138, s67, v214
	v_add_u32_e32 v137, s67, v213
	v_add_u32_e32 v139, s67, v215
	s_waitcnt lgkmcnt(4)
	v_mfma_f32_32x32x16_bf16 v[80:95], v[10:13], v[116:119], v[80:95]
	s_waitcnt lgkmcnt(3)
	v_mfma_f32_32x32x16_bf16 v[96:111], v[128:131], v[120:123], v[96:111]
	s_waitcnt lgkmcnt(2)
	v_mfma_f32_32x32x16_bf16 v[80:95], v[6:9], v[120:123], v[80:95]
	s_waitcnt lgkmcnt(1)
	v_mfma_f32_32x32x16_bf16 v[96:111], v[2:5], v[124:127], v[96:111]
	ds_read_b128 v[6:9], v136 offset:32768
	ds_read_b128 v[2:5], v137 offset:32768
	ds_read_b128 v[10:13], v138 offset:32768
	ds_read_b128 v[128:131], v139 offset:32768
	s_waitcnt lgkmcnt(4)
	v_mfma_f32_32x32x16_bf16 v[80:95], v[132:135], v[124:127], v[80:95]
	s_setprio 1
	s_cmp_lg_u32 s70, 0
	s_cbranch_scc1 .LBB0_436
	v_add_u32_e32 v174, 0xffffff00, v223
	s_nop 0
	v_add_u32_e32 v132, 4, v174
	v_med3_i32 v133, v132, s80, v219
	v_med3_i32 v132, v132, s84, v220
	v_add_u32_e32 v134, 0, v132
	v_add_u32_e32 v132, 8, v174
	v_med3_i32 v135, v132, s80, v219
	v_med3_i32 v132, v132, s84, v220
	v_add_u32_e32 v140, 0, v132
	v_add_u32_e32 v132, 12, v174
	v_med3_i32 v14, v174, s80, v219
	v_med3_i32 v15, v174, s84, v220
	v_med3_i32 v141, v132, s80, v219
	v_add_u32_e32 v14, 0, v14
	v_add_u32_e32 v15, 0, v15
	v_add_u32_e32 v133, 0, v133
	v_add_u32_e32 v135, 0, v135
	v_med3_i32 v132, v132, s84, v220
	v_add_u32_e32 v141, 0, v141
	v_add_u32_e32 v142, 0, v132
	ds_read_b32 v14, v14
	ds_read_b32 v132, v15 offset:128
	ds_read_b32 v15, v133
	ds_read_b32 v133, v134 offset:128
	ds_read_b32 v134, v135
	ds_read_b32 v140, v140 offset:128
	ds_read_b32 v135, v141
	ds_read_b32 v141, v142 offset:128
	v_add_u32_e32 v142, 16, v174
	v_med3_i32 v143, v142, s80, v219
	v_med3_i32 v142, v142, s84, v220
	v_add_u32_e32 v144, 0, v142
	v_add_u32_e32 v142, 20, v174
	v_med3_i32 v145, v142, s80, v219
	v_med3_i32 v142, v142, s84, v220
	v_add_u32_e32 v146, 0, v142
	v_add_u32_e32 v142, 24, v174
	v_med3_i32 v147, v142, s80, v219
	v_med3_i32 v142, v142, s84, v220
	v_add_u32_e32 v164, 0, v142
	v_add_u32_e32 v142, 28, v174
	v_med3_i32 v165, v142, s80, v219
	v_add_u32_e32 v143, 0, v143
	v_add_u32_e32 v145, 0, v145
	v_add_u32_e32 v147, 0, v147
	v_med3_i32 v142, v142, s84, v220
	v_add_u32_e32 v165, 0, v165
	v_add_u32_e32 v166, 0, v142
	ds_read_b32 v142, v143
	ds_read_b32 v144, v144 offset:128
	ds_read_b32 v143, v145
	ds_read_b32 v145, v146 offset:128
	ds_read_b32 v146, v147
	ds_read_b32 v164, v164 offset:128
	ds_read_b32 v147, v165
	ds_read_b32 v165, v166 offset:128
	v_add_u32_e32 v166, 32, v174
	v_med3_i32 v167, v166, s80, v219
	v_med3_i32 v166, v166, s84, v220
	v_add_u32_e32 v168, 0, v166
	v_add_u32_e32 v166, 36, v174
	v_med3_i32 v169, v166, s80, v219
	v_med3_i32 v166, v166, s84, v220
	v_add_u32_e32 v170, 0, v166
	v_add_u32_e32 v166, 40, v174
	v_med3_i32 v171, v166, s80, v219
	v_med3_i32 v166, v166, s84, v220
	v_add_u32_e32 v172, 0, v166
	v_add_u32_e32 v166, 44, v174
	v_med3_i32 v173, v166, s80, v219
	v_add_u32_e32 v167, 0, v167
	v_add_u32_e32 v169, 0, v169
	v_add_u32_e32 v171, 0, v171
	v_med3_i32 v166, v166, s84, v220
	v_add_u32_e32 v173, 0, v173
	v_add_u32_e32 v175, 0, v166
	ds_read_b32 v166, v167
	ds_read_b32 v168, v168 offset:128
	ds_read_b32 v167, v169
	ds_read_b32 v169, v170 offset:128
	ds_read_b32 v170, v171
	ds_read_b32 v172, v172 offset:128
	ds_read_b32 v171, v173
	ds_read_b32 v173, v175 offset:128
	v_add_u32_e32 v175, 48, v174
	v_add_u32_e32 v177, 52, v174
	v_add_u32_e32 v179, 56, v174
	v_add_u32_e32 v174, 60, v174
	v_med3_i32 v176, v175, s80, v219
	v_med3_i32 v181, v174, s80, v219
	v_med3_i32 v174, v174, s84, v220
	v_med3_i32 v175, v175, s84, v220
	v_add_u32_e32 v176, 0, v176
	v_med3_i32 v178, v177, s80, v219
	v_med3_i32 v177, v177, s84, v220
	v_med3_i32 v180, v179, s80, v219
	v_med3_i32 v179, v179, s84, v220
	s_waitcnt lgkmcnt(14)
	v_pk_add_f32 v[98:99], v[98:99], v[134:135]
	v_add_u32_e32 v135, 0, v174
	v_add_u32_e32 v175, 0, v175
	v_add_u32_e32 v178, 0, v178
	v_add_u32_e32 v177, 0, v177
	v_add_u32_e32 v180, 0, v180
	v_add_u32_e32 v179, 0, v179
	v_add_u32_e32 v181, 0, v181
	v_pk_add_f32 v[96:97], v[96:97], v[14:15]
	s_waitcnt lgkmcnt(9)
	v_pk_add_f32 v[102:103], v[102:103], v[146:147]
	v_pk_add_f32 v[100:101], v[100:101], v[142:143]
	ds_read_b32 v14, v176
	ds_read_b32 v134, v175 offset:128
	ds_read_b32 v142, v180
	ds_read_b32 v143, v181
	ds_read_b32 v15, v178
	ds_read_b32 v147, v135 offset:128
	ds_read_b32 v146, v179 offset:128
	ds_read_b32 v135, v177 offset:128
	s_waitcnt lgkmcnt(9)
	v_pk_add_f32 v[106:107], v[106:107], v[170:171]
	v_pk_add_f32 v[104:105], v[104:105], v[166:167]
	s_waitcnt lgkmcnt(4)
	v_pk_add_f32 v[110:111], v[110:111], v[142:143]
	s_waitcnt lgkmcnt(3)
	v_pk_add_f32 v[108:109], v[108:109], v[14:15]
	v_pk_add_f32 v[82:83], v[82:83], v[140:141]
	v_pk_add_f32 v[80:81], v[80:81], v[132:133]
	v_pk_add_f32 v[86:87], v[86:87], v[164:165]
	v_pk_add_f32 v[84:85], v[84:85], v[144:145]
	v_pk_add_f32 v[90:91], v[90:91], v[172:173]
	v_pk_add_f32 v[88:89], v[88:89], v[168:169]
	s_waitcnt lgkmcnt(1)
	v_pk_add_f32 v[94:95], v[94:95], v[146:147]
	s_waitcnt lgkmcnt(0)
	v_pk_add_f32 v[92:93], v[92:93], v[134:135]

; #define LAS __attribute__((address_space(3)))
; __device__ __forceinline__ unsigned cvtpk(float lo, float hi) { f32x2_t v = {lo, hi}; bf16x2_t b = __builtin_convertvector(v, bf16x2_t); return __builtin_bit_cast(unsigned, b); }
; #define SBAR() __builtin_amdgcn_sched_barrier(0)
; template <bool ISSUE> ...
;     ...
;     const unsigned kb_ = (unsigned)(t & 3) * 8192, vb_ = (unsigned)(t & 3) * 16384;
;     bf16x8 kf[8];
; #pragma unroll
;     for (int d0 = 0; d0 < 4; ++d0) { kf[2 * d0] = *(const LAS bf16x8*)(lds + kaddr[d0] + kb_); kf[2 * d0 + 1] = *(const LAS bf16x8*)(lds + kaddr[d0] + kb_ + 4096); }
;     SBAR();
;     const int kt = t * 64;
;     const int rpmin = kt - (qpos_w + 31), rpmax = kt + 63 - qpos_w;
;     const int cls = (rpmax <= -91 ? 1 : (rpmin >= 91 ? 2 : 0));
;     if (cls != cls_cur) { cls_cur = cls; cb = (cls == 0) ? 0.f : (cls == 1 ? bt[0] : bt[258]); }
;     ...
;     const float off = mref - cb;
;     s0 = s0 - off; s1 = s1 - off;
; #pragma unroll
;     for (int r = 0; r < 16; ++r) { s0[r] = __builtin_amdgcn_exp2f(s0[r]); s1[r] = __builtin_amdgcn_exp2f(s1[r]); }
;     {
;         const f32x16 sm = s0 + s1;
;         lsum += ((sm[0] + sm[1]) + (sm[2] + sm[3])) + ((sm[4] + sm[5]) + (sm[6] + sm[7])) + (((sm[8] + sm[9]) + (sm[10] + sm[11])) + ((sm[12] + sm[13]) + (sm[14] + sm[15])));
;     }
;     bf16x8 p[4];
;     {
;         u32x4 w;
;         w.x = cvtpk(s0[0], s0[1]); w.y = cvtpk(s0[2], s0[3]); w.z = cvtpk(s0[4], s0[5]); w.w = cvtpk(s0[6], s0[7]); p[0] = __builtin_bit_cast(bf16x8, w);
;         w.x = cvtpk(s0[8], s0[9]); w.y = cvtpk(s0[10], s0[11]); w.z = cvtpk(s0[12], s0[13]); w.w = cvtpk(s0[14], s0[15]); p[1] = __builtin_bit_cast(bf16x8, w);
;         w.x = cvtpk(s1[0], s1[1]); w.y = cvtpk(s1[2], s1[3]); w.z = cvtpk(s1[4], s1[5]); w.w = cvtpk(s1[6], s1[7]); p[2] = __builtin_bit_cast(bf16x8, w);
;         w.x = cvtpk(s1[8], s1[9]); w.y = cvtpk(s1[10], s1[11]); w.z = cvtpk(s1[12], s1[13]); w.w = cvtpk(s1[14], s1[15]); p[3] = __builtin_bit_cast(bf16x8, w);
;     }
;     v_reads(vb, lds, vaddr, vb_ + 4096);
;     SBAR();
;     pv_rest<128>(o, p, va, vb, lds, vaddr, vb_);
.LBB0_440:
	v_sub_f32_e32 v14, v224, v225
	v_sub_f32_e32 v107, v107, v14
	v_sub_f32_e32 v106, v106, v14
	v_sub_f32_e32 v105, v105, v14
	v_sub_f32_e32 v104, v104, v14
	v_sub_f32_e32 v103, v103, v14
	v_sub_f32_e32 v102, v102, v14
	v_sub_f32_e32 v101, v101, v14
	v_sub_f32_e32 v100, v100, v14
	v_sub_f32_e32 v99, v99, v14
	v_sub_f32_e32 v98, v98, v14
	v_sub_f32_e32 v96, v96, v14
	v_sub_f32_e32 v95, v95, v14
	v_sub_f32_e32 v94, v94, v14
	v_sub_f32_e32 v93, v93, v14
	v_sub_f32_e32 v92, v92, v14
	v_sub_f32_e32 v111, v111, v14
	v_sub_f32_e32 v110, v110, v14
	v_sub_f32_e32 v109, v109, v14
	v_sub_f32_e32 v108, v108, v14
	v_sub_f32_e32 v15, v97, v14
	v_sub_f32_e32 v91, v91, v14
	v_sub_f32_e32 v90, v90, v14
	v_sub_f32_e32 v89, v89, v14
	v_sub_f32_e32 v88, v88, v14
	v_sub_f32_e32 v87, v87, v14
	v_sub_f32_e32 v86, v86, v14
	v_sub_f32_e32 v85, v85, v14
	v_sub_f32_e32 v84, v84, v14
	v_sub_f32_e32 v83, v83, v14
	v_sub_f32_e32 v82, v82, v14
	v_sub_f32_e32 v81, v81, v14
	v_sub_f32_e32 v80, v80, v14
	v_exp_f32_e32 v14, v96
	v_exp_f32_e32 v166, v98
	v_exp_f32_e32 v167, v99
	v_exp_f32_e32 v170, v100
	v_exp_f32_e32 v171, v101
	v_exp_f32_e32 v174, v102
	v_exp_f32_e32 v175, v103
	v_exp_f32_e32 v178, v104
	v_exp_f32_e32 v179, v105
	v_exp_f32_e32 v182, v106
	v_exp_f32_e32 v183, v107
	v_exp_f32_e32 v188, v92
	v_exp_f32_e32 v189, v93
	v_exp_f32_e32 v192, v94
	v_exp_f32_e32 v193, v95
	ds_read_b128 v[92:95], v136 offset:36864
	ds_read_b128 v[96:99], v137 offset:36864
	ds_read_b128 v[100:103], v138 offset:36864
	ds_read_b128 v[104:107], v139 offset:36864
	v_exp_f32_e32 v164, v80
	v_exp_f32_e32 v15, v15
	v_exp_f32_e32 v165, v81
	v_exp_f32_e32 v168, v82
	v_exp_f32_e32 v169, v83
	v_exp_f32_e32 v172, v84
	v_exp_f32_e32 v173, v85
	v_exp_f32_e32 v176, v86
	v_exp_f32_e32 v177, v87
	v_exp_f32_e32 v180, v88
	v_exp_f32_e32 v181, v89
	v_exp_f32_e32 v184, v90
	v_exp_f32_e32 v185, v91
	v_exp_f32_e32 v186, v108
	v_exp_f32_e32 v187, v109
	v_exp_f32_e32 v190, v110
	v_exp_f32_e32 v191, v111
	v_cvt_pk_bf16_f32 v80, v14, v15
	v_cvt_pk_bf16_f32 v81, v166, v167
	v_cvt_pk_bf16_f32 v82, v170, v171
	v_cvt_pk_bf16_f32 v83, v174, v175
	v_cvt_pk_bf16_f32 v84, v178, v179
	v_cvt_pk_bf16_f32 v85, v182, v183
	v_cvt_pk_bf16_f32 v86, v186, v187
	v_cvt_pk_bf16_f32 v87, v190, v191
	v_cvt_pk_bf16_f32 v88, v164, v165
	v_cvt_pk_bf16_f32 v89, v168, v169
	v_cvt_pk_bf16_f32 v90, v172, v173
	v_cvt_pk_bf16_f32 v91, v176, v177
	v_cvt_pk_bf16_f32 v108, v180, v181
	v_cvt_pk_bf16_f32 v109, v184, v185
	v_cvt_pk_bf16_f32 v110, v188, v189
	v_cvt_pk_bf16_f32 v111, v192, v193
	s_setprio 0
	s_waitcnt lgkmcnt(7)
	v_mfma_f32_32x32x16_bf16 v[64:79], v[6:9], v[80:83], v[64:79]
	s_waitcnt lgkmcnt(6)
	v_mfma_f32_32x32x16_bf16 v[64:79], v[2:5], v[84:87], v[64:79]
	s_waitcnt lgkmcnt(5)
	v_mfma_f32_32x32x16_bf16 v[64:79], v[10:13], v[88:91], v[64:79]
	s_waitcnt lgkmcnt(4)
	v_mfma_f32_32x32x16_bf16 v[64:79], v[128:131], v[108:111], v[64:79]
	ds_read_b128 v[2:5], v136 offset:40960
	ds_read_b128 v[6:9], v137 offset:40960
	ds_read_b128 v[10:13], v138 offset:40960
	ds_read_b128 v[128:131], v139 offset:40960
	s_waitcnt lgkmcnt(7)
	v_mfma_f32_32x32x16_bf16 v[48:63], v[92:95], v[80:83], v[48:63]
	s_waitcnt lgkmcnt(6)
	v_mfma_f32_32x32x16_bf16 v[48:63], v[96:99], v[84:87], v[48:63]
	s_waitcnt lgkmcnt(5)
	v_mfma_f32_32x32x16_bf16 v[48:63], v[100:103], v[88:91], v[48:63]
	s_waitcnt lgkmcnt(4)
	v_mfma_f32_32x32x16_bf16 v[48:63], v[104:107], v[108:111], v[48:63]
	ds_read_b128 v[92:95], v136 offset:45056
	ds_read_b128 v[96:99], v137 offset:45056
	ds_read_b128 v[100:103], v138 offset:45056
	ds_read_b128 v[104:107], v139 offset:45056
	s_waitcnt lgkmcnt(7)
	v_mfma_f32_32x32x16_bf16 v[32:47], v[2:5], v[80:83], v[32:47]
	s_waitcnt lgkmcnt(6)
	v_mfma_f32_32x32x16_bf16 v[32:47], v[6:9], v[84:87], v[32:47]
	s_waitcnt lgkmcnt(5)
	v_mfma_f32_32x32x16_bf16 v[32:47], v[10:13], v[88:91], v[32:47]
	s_waitcnt lgkmcnt(4)
	v_mfma_f32_32x32x16_bf16 v[32:47], v[128:131], v[108:111], v[32:47]
	s_waitcnt lgkmcnt(3)
	v_mfma_f32_32x32x16_bf16 v[16:31], v[92:95], v[80:83], v[16:31]
	s_add_i32 s11, s8, -2
	s_and_b32 s11, s11, 3
	s_lshl_b32 s67, s11, 13
	s_add_i32 s70, s67, 0
	v_add_u32_e32 v6, s70, v206
	v_add_u32_e32 v10, s70, v207
	ds_read_b128 v[2:5], v6
	ds_read_b128 v[6:9], v6 offset:4096
	s_waitcnt lgkmcnt(4)
	v_mfma_f32_32x32x16_bf16 v[16:31], v[96:99], v[84:87], v[16:31]
	ds_read_b128 v[144:147], v10
	ds_read_b128 v[136:139], v10 offset:4096
	v_add_u32_e32 v10, s70, v208
	v_add_u32_e32 v80, s70, v209
	ds_read_b128 v[140:143], v10
	ds_read_b128 v[128:131], v10 offset:4096
	ds_read_b128 v[10:13], v80
	ds_read_b128 v[132:135], v80 offset:4096
	s_waitcnt lgkmcnt(9)
	v_mfma_f32_32x32x16_bf16 v[16:31], v[100:103], v[88:91], v[16:31]
	s_waitcnt lgkmcnt(8)
	v_mfma_f32_32x32x16_bf16 v[16:31], v[104:107], v[108:111], v[16:31]
	s_add_i32 s11, s53, 31
	s_cmpk_gt_i32 s53, 0x5a
	s_cselect_b32 s62, 2, 0
	s_cmpk_gt_i32 s11, 0xff66
	s_cselect_b32 s71, s62, 1
	s_cmp_eq_u32 s71, s10
	s_cbranch_scc1 .LBB0_446
	s_cmp_lt_i32 s71, 1
	v_mov_b32_e32 v225, 0
	s_mov_b32 s10, s71
	s_cbranch_scc1 .LBB0_446
	s_cmp_lg_u32 s71, 1
	s_cbranch_scc0 .LBB0_444
	v_mov_b32_e32 v80, s83
	ds_read_b32 v225, v80
	s_mov_b32 s10, 2
	s_cbranch_execz .LBB0_445
	s_branch .LBB0_446

; #define LAS __attribute__((address_space(3)))
; #define SBAR() __builtin_amdgcn_sched_barrier(0)
; template <bool ISSUE> ...
;     ...
;     f32x16 s0, s1;
;     s0 = __builtin_amdgcn_mfma_f32_32x32x16_bf16(kf[0], qf[0], f32x16{}, 0, 0, 0);
;     s1 = __builtin_amdgcn_mfma_f32_32x32x16_bf16(kf[1], qf[0], f32x16{}, 0, 0, 0);
; #pragma unroll
;     for (int d0 = 1; d0 < 4; ++d0) {
;         s0 = __builtin_amdgcn_mfma_f32_32x32x16_bf16(kf[2 * d0], qf[d0], s0, 0, 0, 0);
;         s1 = __builtin_amdgcn_mfma_f32_32x32x16_bf16(kf[2 * d0 + 1], qf[d0], s1, 0, 0, 0);
;     }
;     bf16x8 va[4], vb[4];
;     v_reads(va, lds, vaddr, vb_);
;     SBAR();
;     if (cls == 0) {
;         int a0 = (kt + 16 * hi - (qpos_w + r32) + 129) * 4 + A_BT; asm volatile("" : "+v"(a0));
; #pragma unroll
;         for (int rg = 0; rg < 4; ++rg) {
; #pragma unroll
;             for (int r = 4 * rg; r < 4 * rg + 4; ++r) {
;                 const int aa = min(max(a0 + 4 * r, A_BT), A_BT + 258 * 4), ab = min(max(a0 + 4 * r + 128, A_BT), A_BT + 258 * 4);
;                 s0[r] += *(const LAS float*)(lds + aa);
;                 s1[r] += *(const LAS float*)(lds + ab);
;             }
;             SBAR();
;         }
.LBB0_446:
	s_waitcnt lgkmcnt(7)
	v_mfma_f32_32x32x16_bf16 v[96:111], v[2:5], v[112:115], 0
	s_add_i32 s70, s70, s67
	s_waitcnt lgkmcnt(6)
	v_mfma_f32_32x32x16_bf16 v[80:95], v[6:9], v[112:115], 0
	s_waitcnt lgkmcnt(5)
	v_mfma_f32_32x32x16_bf16 v[96:111], v[144:147], v[116:119], v[96:111]
	s_waitcnt lgkmcnt(4)
	v_mfma_f32_32x32x16_bf16 v[80:95], v[136:139], v[116:119], v[80:95]
	v_add_u32_e32 v136, s70, v212
	v_add_u32_e32 v138, s70, v214
	v_add_u32_e32 v137, s70, v213
	ds_read_b128 v[6:9], v136 offset:32768
	ds_read_b128 v[2:5], v137 offset:32768
	v_add_u32_e32 v139, s70, v215
	s_waitcnt lgkmcnt(5)
	v_mfma_f32_32x32x16_bf16 v[96:111], v[140:143], v[120:123], v[96:111]
	s_waitcnt lgkmcnt(4)
	v_mfma_f32_32x32x16_bf16 v[80:95], v[128:131], v[120:123], v[80:95]
	s_waitcnt lgkmcnt(3)
	v_mfma_f32_32x32x16_bf16 v[96:111], v[10:13], v[124:127], v[96:111]
	ds_read_b128 v[10:13], v138 offset:32768
	ds_read_b128 v[128:131], v139 offset:32768
	s_waitcnt lgkmcnt(4)
	v_mfma_f32_32x32x16_bf16 v[80:95], v[132:135], v[124:127], v[80:95]
	s_setprio 1
	s_cmp_lg_u32 s71, 0
	s_cbranch_scc1 .LBB0_448
	v_mov_b32_e32 v238, v223
	s_nop 0
	v_add_u32_e32 v134, 4, v238
	v_med3_i32 v135, v134, s80, v219
	v_med3_i32 v134, v134, s84, v220
	v_add_u32_e32 v140, 0, v134
	v_add_u32_e32 v134, 8, v238
	v_med3_i32 v141, v134, s80, v219
	v_med3_i32 v134, v134, s84, v220
	v_add_u32_e32 v142, 0, v134
	v_add_u32_e32 v134, 12, v238
	v_med3_i32 v132, v238, s80, v219
	v_med3_i32 v133, v238, s84, v220
	v_med3_i32 v143, v134, s80, v219
	v_add_u32_e32 v132, 0, v132
	v_add_u32_e32 v133, 0, v133
	v_add_u32_e32 v135, 0, v135
	v_add_u32_e32 v141, 0, v141
	v_med3_i32 v134, v134, s84, v220
	v_add_u32_e32 v143, 0, v143
	v_add_u32_e32 v144, 0, v134
	ds_read_b32 v132, v132
	ds_read_b32 v134, v133 offset:128
	ds_read_b32 v133, v135
	ds_read_b32 v135, v140 offset:128
	ds_read_b32 v140, v141
	ds_read_b32 v142, v142 offset:128
	ds_read_b32 v141, v143
	ds_read_b32 v143, v144 offset:128
	v_add_u32_e32 v144, 16, v238
	v_med3_i32 v145, v144, s80, v219
	v_med3_i32 v144, v144, s84, v220
	v_add_u32_e32 v146, 0, v144
	v_add_u32_e32 v144, 20, v238
	v_med3_i32 v147, v144, s80, v219
	v_med3_i32 v144, v144, s84, v220
	v_add_u32_e32 v226, 0, v144
	v_add_u32_e32 v144, 24, v238
	v_med3_i32 v227, v144, s80, v219
	v_med3_i32 v144, v144, s84, v220
	v_add_u32_e32 v228, 0, v144
	v_add_u32_e32 v144, 28, v238
	v_med3_i32 v229, v144, s80, v219
	v_add_u32_e32 v145, 0, v145
	v_add_u32_e32 v147, 0, v147
	v_add_u32_e32 v227, 0, v227
	v_med3_i32 v144, v144, s84, v220
	v_add_u32_e32 v229, 0, v229
	v_add_u32_e32 v230, 0, v144
	ds_read_b32 v144, v145
	ds_read_b32 v146, v146 offset:128
	ds_read_b32 v145, v147
	ds_read_b32 v147, v226 offset:128
	ds_read_b32 v226, v227
	ds_read_b32 v228, v228 offset:128
	ds_read_b32 v227, v229
	ds_read_b32 v229, v230 offset:128
	v_add_u32_e32 v230, 32, v238
	v_med3_i32 v231, v230, s80, v219
	v_med3_i32 v230, v230, s84, v220
	v_add_u32_e32 v232, 0, v230
	v_add_u32_e32 v230, 36, v238
	v_med3_i32 v233, v230, s80, v219
	v_med3_i32 v230, v230, s84, v220
	v_add_u32_e32 v234, 0, v230
	v_add_u32_e32 v230, 40, v238
	v_med3_i32 v235, v230, s80, v219
	v_med3_i32 v230, v230, s84, v220
	v_add_u32_e32 v236, 0, v230
	v_add_u32_e32 v230, 44, v238
	v_med3_i32 v237, v230, s80, v219
	v_add_u32_e32 v231, 0, v231
	v_add_u32_e32 v233, 0, v233
	v_add_u32_e32 v235, 0, v235
	v_med3_i32 v230, v230, s84, v220
	v_add_u32_e32 v237, 0, v237
	v_add_u32_e32 v239, 0, v230
	ds_read_b32 v230, v231
	ds_read_b32 v232, v232 offset:128
	ds_read_b32 v231, v233
	ds_read_b32 v233, v234 offset:128
	ds_read_b32 v234, v235
	ds_read_b32 v236, v236 offset:128
	ds_read_b32 v235, v237
	ds_read_b32 v237, v239 offset:128
	v_add_u32_e32 v239, 48, v238
	v_add_u32_e32 v241, 52, v238
	v_add_u32_e32 v243, 56, v238
	v_add_u32_e32 v238, 60, v238
	v_med3_i32 v240, v239, s80, v219
	v_med3_i32 v245, v238, s80, v219
	v_med3_i32 v238, v238, s84, v220
	v_med3_i32 v239, v239, s84, v220
	v_add_u32_e32 v240, 0, v240
	v_med3_i32 v242, v241, s80, v219
	v_med3_i32 v241, v241, s84, v220
	v_med3_i32 v244, v243, s80, v219
	v_med3_i32 v243, v243, s84, v220
	s_waitcnt lgkmcnt(14)
	v_pk_add_f32 v[98:99], v[98:99], v[140:141]
	v_add_u32_e32 v141, 0, v238
	v_add_u32_e32 v239, 0, v239
	v_add_u32_e32 v242, 0, v242
	v_add_u32_e32 v241, 0, v241
	v_add_u32_e32 v244, 0, v244
	v_add_u32_e32 v243, 0, v243
	v_add_u32_e32 v245, 0, v245
	v_pk_add_f32 v[96:97], v[96:97], v[132:133]
	s_waitcnt lgkmcnt(9)
	v_pk_add_f32 v[102:103], v[102:103], v[226:227]
	v_pk_add_f32 v[100:101], v[100:101], v[144:145]
	ds_read_b32 v132, v240
	ds_read_b32 v140, v239 offset:128
	ds_read_b32 v144, v244
	ds_read_b32 v145, v245
	ds_read_b32 v133, v242
	ds_read_b32 v227, v141 offset:128
	ds_read_b32 v226, v243 offset:128
	ds_read_b32 v141, v241 offset:128
	s_waitcnt lgkmcnt(9)
	v_pk_add_f32 v[106:107], v[106:107], v[234:235]
	v_pk_add_f32 v[104:105], v[104:105], v[230:231]
	s_waitcnt lgkmcnt(4)
	v_pk_add_f32 v[110:111], v[110:111], v[144:145]
	s_waitcnt lgkmcnt(3)
	v_pk_add_f32 v[108:109], v[108:109], v[132:133]
	v_pk_add_f32 v[82:83], v[82:83], v[142:143]
	v_pk_add_f32 v[80:81], v[80:81], v[134:135]
	v_pk_add_f32 v[86:87], v[86:87], v[228:229]
	v_pk_add_f32 v[84:85], v[84:85], v[146:147]
	v_pk_add_f32 v[90:91], v[90:91], v[236:237]
	v_pk_add_f32 v[88:89], v[88:89], v[232:233]
	s_waitcnt lgkmcnt(1)
	v_pk_add_f32 v[94:95], v[94:95], v[226:227]
	s_waitcnt lgkmcnt(0)
	v_pk_add_f32 v[92:93], v[92:93], v[140:141]
